# code placement: also the attention tile-loop latch, SSD-out stage-3 loop and states MFMA loop heads pinned to 64-byte boundaries; on top of the aligned-GEMM-loops version
# speedup vs baseline: 1.0039x; 1.0034x over previous
; template <class Put>
; __device__ __forceinline__ void conv_compute(const ConvRaw& R, const float* cw, const float* cb, int col0, int rg, const Put& put) {
;     const f32x4 w0a = *(const f32x4*)(cw + col0), w0b = *(const f32x4*)(cw + col0 + 4), w1a = *(const f32x4*)(cw + XBCW + col0), w1b = *(const f32x4*)(cw + XBCW + col0 + 4);
;     const f32x4 w2a = *(const f32x4*)(cw + 2 * XBCW + col0), w2b = *(const f32x4*)(cw + 2 * XBCW + col0 + 4), ba = *(const f32x4*)(cb + col0), bb = *(const f32x4*)(cb + col0 + 4);
;     const int r0 = 8 * rg;
; #pragma unroll
;     for (int rr = 0; rr < 8; ++rr) {
;         const u32x4 xm = R.r[rr], x0 = R.r[rr + 1], xp = R.r[rr + 2]; u32x4 o;
; #pragma unroll
;         for (int e = 0; e < 4; ++e) {
;             const float wl0 = e < 2 ? w0a[2 * e] : w0b[2 * e - 4], wh0 = e < 2 ? w0a[2 * e + 1] : w0b[2 * e - 3];
;             const float wl1 = e < 2 ? w1a[2 * e] : w1b[2 * e - 4], wh1 = e < 2 ? w1a[2 * e + 1] : w1b[2 * e - 3];
;             const float wl2 = e < 2 ? w2a[2 * e] : w2b[2 * e - 4], wh2 = e < 2 ? w2a[2 * e + 1] : w2b[2 * e - 3];
;             const float bl = e < 2 ? ba[2 * e] : bb[2 * e - 4], bh = e < 2 ? ba[2 * e + 1] : bb[2 * e - 3];
;             const float vl = bl + wl0 * lo16(xm[e]) + wl1 * lo16(x0[e]) + wl2 * lo16(xp[e]);
;             const float vh = bh + wh0 * hi16(xm[e]) + wh1 * hi16(x0[e]) + wh2 * hi16(xp[e]);
;             o[e] = cvtpk(silu_fast(vl), silu_fast(vh));
;         }
;         put(r0 + rr, o);
;     }
; }
; __device__ __forceinline__ void states_unit(Frame& F, const Ptrs& P, int b, int c, int g, int hh) {
;     ...
;         ConvRawN<4> Rb; ConvRaw Rx; const int chb = tid & 15, rgb = tid >> 4, hlx = tid >> 7, chx = tid & 7, rgx = (tid >> 3) & 15;
;         conv_load_n<4>(Rb, XBC, b, c, 1024 + g * 128 + 8 * chb, rgb);
;         conv_load(Rx, XBC, b, c, (h0 + hlx) * 64 + 8 * chx, rgx);
;         if (wid == 0 && lane == 0) { const unsigned* fl = (const unsigned*)(P.ws + WS_CTL) + CW_DTF + (b * 128 + 2 * c); unsigned sp = 0u;
;             while ((__hip_atomic_load(fl, __ATOMIC_RELAXED, __HIP_MEMORY_SCOPE_AGENT) & __hip_atomic_load(fl + 1, __ATOMIC_RELAXED, __HIP_MEMORY_SCOPE_AGENT)) == 0u) { __builtin_amdgcn_s_sleep(1); if (++sp > (1u << 22)) break; } }
;         __syncthreads();
;         float dv0, dv1; vec_load(F, P, b, c, h0, dv0, dv1);
.LBB0_577:
	s_or_b64 exec, exec, s[0:1]
	v_lshlrev_b64 v[44:45], 2, v[96:97]
	v_lshl_add_u64 v[46:47], s[24:25], 0, v[44:45]
	global_load_dwordx4 v[40:43], v[46:47], off offset:16
	global_load_dwordx4 v[56:59], v[46:47], off
	v_lshl_add_u64 v[46:47], s[26:27], 0, v[44:45]
	global_load_dwordx4 v[60:63], v[46:47], off
	global_load_dwordx4 v[48:51], v[46:47], off offset:16
	v_lshl_add_u64 v[46:47], s[22:23], 0, v[44:45]
	global_load_dwordx4 v[64:67], v[46:47], off
	global_load_dwordx4 v[52:55], v[46:47], off offset:16
	v_lshl_add_u64 v[44:45], s[28:29], 0, v[44:45]
	global_load_dwordx4 v[68:71], v[44:45], off
	s_nop 0
	global_load_dwordx4 v[44:47], v[44:45], off offset:16
	global_load_dwordx4 v[188:191], v[146:147], off
	global_load_dwordx4 v[192:195], v[148:149], off
	global_load_dwordx4 v[196:199], v[150:151], off
	global_load_dwordx4 v[200:203], v[152:153], off
	global_load_dwordx4 v[204:207], v[154:155], off
	global_load_dwordx4 v[208:211], v[156:157], off
	global_load_dwordx4 v[212:215], v[158:159], off
	global_load_dwordx4 v[216:219], v[160:161], off
	global_load_dwordx4 v[220:223], v[162:163], off
	global_load_dwordx4 v[224:227], v[164:165], off
	global_load_dwordx4 v[228:231], v[166:167], off
	global_load_dwordx4 v[232:235], v[168:169], off
	global_load_dwordx4 v[236:239], v[170:171], off
	global_load_dwordx4 v[240:243], v[172:173], off
	global_load_dwordx4 v[244:247], v[174:175], off
	global_load_dwordx4 v[248:251], v[176:177], off
	v_or_b32_e32 v80, s84, v102
	v_cmp_eq_u32_e32 vcc, 15, v102
	v_lshlrev_b32_e32 v82, 1, v101
	v_lshrrev_b32_e32 v83, 1, v102
	v_cmp_ne_u32_e64 s[0:1], 0, v80
	v_lshlrev_b32_e32 v74, 16, v24
	v_and_b32_e32 v75, 0xffff0000, v24
	v_lshlrev_b32_e32 v72, 16, v28
	v_and_b32_e32 v73, 0xffff0000, v28
	v_lshlrev_b32_e32 v76, 16, v25
	v_and_b32_e32 v77, 0xffff0000, v25
	v_lshlrev_b32_e32 v24, 16, v29
	v_and_b32_e32 v25, 0xffff0000, v29
	v_lshlrev_b32_e32 v28, 16, v30
	v_and_b32_e32 v29, 0xffff0000, v30
	v_cndmask_b32_e64 v30, 0, v35, s[0:1]
	s_and_b64 s[4:5], s[72:73], vcc
	v_and_or_b32 v35, v82, 8, v83
	v_lshlrev_b32_e32 v81, 14, v103
	v_lshlrev_b32_e32 v78, 16, v26
	v_and_b32_e32 v79, 0xffff0000, v26
	v_cndmask_b32_e64 v26, v39, 0, s[4:5]
	v_cndmask_b32_e64 v83, 0, v34, s[0:1]
	v_cndmask_b32_e64 v82, 0, v33, s[0:1]
	v_cndmask_b32_e64 v39, 0, v32, s[0:1]
	v_lshlrev_b32_e32 v35, 10, v35
	v_cndmask_b32_e64 v32, v38, 0, s[4:5]
	v_cndmask_b32_e64 v33, v37, 0, s[4:5]
	v_cndmask_b32_e64 v34, v36, 0, s[4:5]
	v_lshlrev_b32_e32 v36, 16, v30
	v_and_b32_e32 v37, 0xffff0000, v30
	v_add3_u32 v30, s82, v81, v35
	v_lshlrev_b32_e32 v38, 16, v39
	v_and_b32_e32 v39, 0xffff0000, v39
	v_lshlrev_b32_e32 v80, 16, v82
	v_and_b32_e32 v81, 0xffff0000, v82
	v_lshlrev_b32_e32 v82, 16, v83
	v_and_b32_e32 v83, 0xffff0000, v83
	v_lshlrev_b32_e32 v84, 9, v102
	v_lshlrev_b32_e32 v85, 4, v101
	v_and_b32_e32 v84, 0x200, v84
	v_and_b32_e32 v85, 48, v85
	v_add3_u32 v30, v30, v84, v85
	v_lshrrev_b32_e32 v128, 5, v104
	v_lshlrev_b32_e32 v141, 4, v100
	s_mov_b32 s2, 0
	v_lshl_add_u32 v142, v128, 4, 0
	s_waitcnt vmcnt(21)
	v_pk_fma_f32 v[38:39], v[56:57], v[38:39], v[60:61]
	v_pk_fma_f32 v[80:81], v[58:59], v[80:81], v[62:63]
	s_waitcnt vmcnt(20)
	v_pk_fma_f32 v[82:83], v[40:41], v[82:83], v[48:49]
	s_waitcnt vmcnt(19)
	v_pk_fma_f32 v[38:39], v[64:65], v[74:75], v[38:39]
	v_pk_fma_f32 v[80:81], v[66:67], v[76:77], v[80:81]
	s_waitcnt vmcnt(18)
	v_pk_fma_f32 v[82:83], v[52:53], v[78:79], v[82:83]
	s_waitcnt vmcnt(17)
	v_pk_fma_f32 v[38:39], v[68:69], v[72:73], v[38:39]
	v_pk_fma_f32 v[80:81], v[70:71], v[24:25], v[80:81]
	s_waitcnt vmcnt(16)
	v_pk_fma_f32 v[82:83], v[44:45], v[28:29], v[82:83]
	v_mul_f32_e32 v35, 0xbfb8aa3b, v38
	v_mul_f32_e32 v84, 0xbfb8aa3b, v39
	v_mul_f32_e32 v85, 0xbfb8aa3b, v80
	v_mul_f32_e32 v86, 0xbfb8aa3b, v81
	v_mul_f32_e32 v87, 0xbfb8aa3b, v82
	v_mul_f32_e32 v88, 0xbfb8aa3b, v83
	v_exp_f32_e32 v35, v35
	v_exp_f32_e32 v84, v84
	v_exp_f32_e32 v85, v85
	v_exp_f32_e32 v86, v86
	v_exp_f32_e32 v87, v87
	v_exp_f32_e32 v88, v88
	v_add_f32_e32 v35, 1.0, v35
	v_add_f32_e32 v89, 1.0, v84
	v_add_f32_e32 v90, 1.0, v85
	v_add_f32_e32 v91, 1.0, v86
	v_add_f32_e32 v92, 1.0, v87
	v_add_f32_e32 v93, 1.0, v88
	v_rcp_f32_e32 v84, v35
	v_rcp_f32_e32 v85, v89
	v_rcp_f32_e32 v86, v90
	v_rcp_f32_e32 v87, v91
	v_rcp_f32_e32 v88, v92
	v_rcp_f32_e32 v89, v93
	v_pk_fma_f32 v[90:91], v[42:43], v[36:37], v[50:51]
	v_pk_mul_f32 v[36:37], v[38:39], v[84:85]
	v_pk_mul_f32 v[38:39], v[80:81], v[86:87]
	v_pk_mul_f32 v[80:81], v[82:83], v[88:89]
	v_lshlrev_b32_e32 v82, 16, v27
	v_and_b32_e32 v83, 0xffff0000, v27
	v_cvt_pk_bf16_f32 v36, v36, v37
	v_cvt_pk_bf16_f32 v37, v38, v39
	v_pk_fma_f32 v[38:39], v[54:55], v[82:83], v[90:91]
	v_lshlrev_b32_e32 v84, 16, v31
	v_and_b32_e32 v85, 0xffff0000, v31
	v_pk_fma_f32 v[86:87], v[46:47], v[84:85], v[38:39]
	v_pk_fma_f32 v[74:75], v[56:57], v[74:75], v[60:61]
	v_mul_f32_e32 v27, 0xbfb8aa3b, v86
	v_exp_f32_e32 v27, v27
	v_mul_f32_e32 v31, 0xbfb8aa3b, v87
	v_exp_f32_e32 v31, v31
	v_pk_fma_f32 v[74:75], v[64:65], v[72:73], v[74:75]
	v_lshlrev_b32_e32 v88, 16, v20
	v_and_b32_e32 v89, 0xffff0000, v20
	v_pk_fma_f32 v[74:75], v[68:69], v[88:89], v[74:75]
	v_add_f32_e32 v27, 1.0, v27
	v_mul_f32_e32 v20, 0xbfb8aa3b, v74
	v_cvt_pk_bf16_f32 v38, v80, v81
	v_rcp_f32_e32 v80, v27
	v_add_f32_e32 v27, 1.0, v31
	v_exp_f32_e32 v20, v20
	v_mul_f32_e32 v31, 0xbfb8aa3b, v75
	v_exp_f32_e32 v31, v31
	v_rcp_f32_e32 v81, v27
	v_add_f32_e32 v20, 1.0, v20
	v_rcp_f32_e32 v90, v20
	v_add_f32_e32 v20, 1.0, v31
	v_rcp_f32_e32 v91, v20
	v_pk_mul_f32 v[80:81], v[86:87], v[80:81]
	s_nop 0
	v_cvt_pk_bf16_f32 v39, v80, v81
	ds_write_b128 v30, v[36:39]
; __device__ __forceinline__ unsigned cvtpk(float lo, float hi) { f32x2_t v = {lo, hi}; bf16x2_t b = __builtin_convertvector(v, bf16x2_t); return __builtin_bit_cast(unsigned, b); }
; __device__ __forceinline__ float lo16(unsigned u) { return __uint_as_float(u << 16); }
; __device__ __forceinline__ float hi16(unsigned u) { return __uint_as_float(u & 0xffff0000u); }
; __device__ __forceinline__ float silu_fast(float v) { return v * __builtin_amdgcn_rcpf(1.f + __builtin_amdgcn_exp2f(-v * LOG2E)); }
; __device__ __forceinline__ unsigned cvtpk(float lo, float hi) { f32x2_t v = {lo, hi}; bf16x2_t b = __builtin_convertvector(v, bf16x2_t); return __builtin_bit_cast(unsigned, b); }
; __device__ __forceinline__ float lo16(unsigned u) { return __uint_as_float(u << 16); }
; __device__ __forceinline__ float hi16(unsigned u) { return __uint_as_float(u & 0xffff0000u); }
; __device__ __forceinline__ float silu_fast(float v) { return v * __builtin_amdgcn_rcpf(1.f + __builtin_amdgcn_exp2f(-v * LOG2E)); }
; template <class Put>
; __device__ __forceinline__ void conv_compute(const ConvRaw& R, const float* cw, const float* cb, int col0, int rg, const Put& put) {
;     ...
;     for (int rr = 0; rr < 8; ++rr) {
;         const u32x4 xm = R.r[rr], x0 = R.r[rr + 1], xp = R.r[rr + 2]; u32x4 o;
; #pragma unroll
;         for (int e = 0; e < 4; ++e) {
;             const float wl0 = e < 2 ? w0a[2 * e] : w0b[2 * e - 4], wh0 = e < 2 ? w0a[2 * e + 1] : w0b[2 * e - 3];
;             const float wl1 = e < 2 ? w1a[2 * e] : w1b[2 * e - 4], wh1 = e < 2 ? w1a[2 * e + 1] : w1b[2 * e - 3];
;             const float wl2 = e < 2 ? w2a[2 * e] : w2b[2 * e - 4], wh2 = e < 2 ? w2a[2 * e + 1] : w2b[2 * e - 3];
;             const float bl = e < 2 ? ba[2 * e] : bb[2 * e - 4], bh = e < 2 ? ba[2 * e + 1] : bb[2 * e - 3];
;             const float vl = bl + wl0 * lo16(xm[e]) + wl1 * lo16(x0[e]) + wl2 * lo16(xp[e]);
;             const float vh = bh + wh0 * hi16(xm[e]) + wh1 * hi16(x0[e]) + wh2 * hi16(xp[e]);
;             o[e] = cvtpk(silu_fast(vl), silu_fast(vh));
;         }
;         put(r0 + rr, o);
;     }
	v_pk_fma_f32 v[38:39], v[58:59], v[76:77], v[62:63]
	v_pk_mul_f32 v[36:37], v[74:75], v[90:91]
	v_pk_fma_f32 v[38:39], v[66:67], v[24:25], v[38:39]
	v_lshlrev_b32_e32 v74, 16, v21
	v_and_b32_e32 v75, 0xffff0000, v21
	v_pk_fma_f32 v[38:39], v[70:71], v[74:75], v[38:39]
	v_pk_fma_f32 v[76:77], v[40:41], v[78:79], v[48:49]
	v_mul_f32_e32 v20, 0xbfb8aa3b, v38
	v_exp_f32_e32 v21, v20
	v_mul_f32_e32 v20, 0xbfb8aa3b, v39
	v_exp_f32_e32 v27, v20
	v_cvt_pk_bf16_f32 v20, v36, v37
	v_add_f32_e32 v21, 1.0, v21
	v_rcp_f32_e32 v36, v21
	v_add_f32_e32 v21, 1.0, v27
	v_rcp_f32_e32 v37, v21
	v_pk_fma_f32 v[76:77], v[52:53], v[28:29], v[76:77]
	v_lshlrev_b32_e32 v78, 16, v22
	v_and_b32_e32 v79, 0xffff0000, v22
	v_pk_fma_f32 v[76:77], v[44:45], v[78:79], v[76:77]
	v_pk_mul_f32 v[36:37], v[38:39], v[36:37]
	v_mul_f32_e32 v21, 0xbfb8aa3b, v76
	v_exp_f32_e32 v21, v21
	v_mul_f32_e32 v22, 0xbfb8aa3b, v77
	v_exp_f32_e32 v27, v22
	v_pk_fma_f32 v[38:39], v[42:43], v[82:83], v[50:51]
	v_lshlrev_b32_e32 v80, 16, v23
	v_pk_fma_f32 v[38:39], v[54:55], v[84:85], v[38:39]
	v_and_b32_e32 v81, 0xffff0000, v23
	v_pk_fma_f32 v[38:39], v[46:47], v[80:81], v[38:39]
	v_add_f32_e32 v21, 1.0, v21
	v_mul_f32_e32 v23, 0xbfb8aa3b, v38
	v_rcp_f32_e32 v22, v21
	v_add_f32_e32 v21, 1.0, v27
	v_exp_f32_e32 v27, v23
	v_mul_f32_e32 v23, 0xbfb8aa3b, v39
	v_exp_f32_e32 v31, v23
	v_rcp_f32_e32 v23, v21
	v_add_f32_e32 v21, 1.0, v27
	v_rcp_f32_e32 v82, v21
	v_add_f32_e32 v21, 1.0, v31
	v_rcp_f32_e32 v83, v21
	v_cvt_pk_bf16_f32 v21, v36, v37
	v_pk_mul_f32 v[22:23], v[76:77], v[22:23]
	v_pk_fma_f32 v[28:29], v[40:41], v[28:29], v[48:49]
	v_pk_mul_f32 v[36:37], v[38:39], v[82:83]
	v_cvt_pk_bf16_f32 v22, v22, v23
	v_cvt_pk_bf16_f32 v23, v36, v37
	v_pk_fma_f32 v[36:37], v[56:57], v[72:73], v[60:61]
	v_lshlrev_b32_e32 v38, 16, v16
	v_pk_fma_f32 v[36:37], v[64:65], v[88:89], v[36:37]
	v_and_b32_e32 v39, 0xffff0000, v16
	v_pk_fma_f32 v[36:37], v[68:69], v[38:39], v[36:37]
	ds_write_b128 v30, v[20:23] offset:64
	v_mul_f32_e32 v16, 0xbfb8aa3b, v36
	v_exp_f32_e32 v16, v16
	v_mul_f32_e32 v27, 0xbfb8aa3b, v37
	v_exp_f32_e32 v27, v27
	v_pk_fma_f32 v[22:23], v[58:59], v[24:25], v[62:63]
	v_add_f32_e32 v16, 1.0, v16
	v_rcp_f32_e32 v20, v16
	v_add_f32_e32 v16, 1.0, v27
	v_rcp_f32_e32 v21, v16
	v_pk_fma_f32 v[22:23], v[66:67], v[74:75], v[22:23]
	v_lshlrev_b32_e32 v24, 16, v17
	v_and_b32_e32 v25, 0xffff0000, v17
	v_pk_fma_f32 v[22:23], v[70:71], v[24:25], v[22:23]
	v_pk_fma_f32 v[28:29], v[52:53], v[78:79], v[28:29]
	v_mul_f32_e32 v16, 0xbfb8aa3b, v22
	v_exp_f32_e32 v27, v16
	v_mul_f32_e32 v16, 0xbfb8aa3b, v23
	v_exp_f32_e32 v31, v16
	v_pk_mul_f32 v[16:17], v[36:37], v[20:21]
	v_lshlrev_b32_e32 v36, 16, v18
	v_and_b32_e32 v37, 0xffff0000, v18
	v_pk_fma_f32 v[28:29], v[44:45], v[36:37], v[28:29]
	v_add_f32_e32 v20, 1.0, v27
	v_mul_f32_e32 v18, 0xbfb8aa3b, v28
	v_exp_f32_e32 v18, v18
	v_mul_f32_e32 v27, 0xbfb8aa3b, v29
	v_exp_f32_e32 v27, v27
	v_add_f32_e32 v21, 1.0, v31
	v_add_f32_e32 v18, 1.0, v18
	v_rcp_f32_e32 v20, v20
	v_rcp_f32_e32 v21, v21
	v_rcp_f32_e32 v72, v18
	v_add_f32_e32 v18, 1.0, v27
	v_rcp_f32_e32 v73, v18
	v_pk_mul_f32 v[20:21], v[22:23], v[20:21]
	v_pk_fma_f32 v[22:23], v[42:43], v[84:85], v[50:51]
	v_cvt_pk_bf16_f32 v16, v16, v17
	v_cvt_pk_bf16_f32 v17, v20, v21
	v_pk_mul_f32 v[20:21], v[28:29], v[72:73]
	v_pk_fma_f32 v[22:23], v[54:55], v[80:81], v[22:23]
	v_lshlrev_b32_e32 v28, 16, v19
	v_and_b32_e32 v29, 0xffff0000, v19
	v_pk_fma_f32 v[22:23], v[46:47], v[28:29], v[22:23]
	v_pk_fma_f32 v[72:73], v[56:57], v[88:89], v[60:61]
	v_mul_f32_e32 v18, 0xbfb8aa3b, v22
	v_exp_f32_e32 v19, v18
	v_mul_f32_e32 v18, 0xbfb8aa3b, v23
	v_exp_f32_e32 v27, v18
	v_pk_fma_f32 v[72:73], v[64:65], v[38:39], v[72:73]
	v_lshlrev_b32_e32 v76, 16, v12
	v_and_b32_e32 v77, 0xffff0000, v12
	v_add_f32_e32 v19, 1.0, v19
	v_pk_fma_f32 v[72:73], v[68:69], v[76:77], v[72:73]
	v_cvt_pk_bf16_f32 v18, v20, v21
	v_rcp_f32_e32 v20, v19
	v_add_f32_e32 v19, 1.0, v27
	v_mul_f32_e32 v21, 0xbfb8aa3b, v73
	v_exp_f32_e32 v27, v21
	v_rcp_f32_e32 v21, v19
	v_mul_f32_e32 v12, 0xbfb8aa3b, v72
	v_exp_f32_e32 v12, v12
	v_pk_mul_f32 v[20:21], v[22:23], v[20:21]
	s_nop 0
	v_cvt_pk_bf16_f32 v19, v20, v21
	ds_write_b128 v30, v[16:19] offset:128
	v_pk_fma_f32 v[18:19], v[58:59], v[74:75], v[62:63]
	v_add_f32_e32 v12, 1.0, v12
	v_pk_fma_f32 v[18:19], v[66:67], v[24:25], v[18:19]
	v_lshlrev_b32_e32 v20, 16, v13
	v_and_b32_e32 v21, 0xffff0000, v13
	v_rcp_f32_e32 v82, v12
	v_add_f32_e32 v12, 1.0, v27
	v_pk_fma_f32 v[18:19], v[70:71], v[20:21], v[18:19]
	v_rcp_f32_e32 v83, v12
	v_mul_f32_e32 v12, 0xbfb8aa3b, v18
	v_exp_f32_e32 v13, v12
	v_mul_f32_e32 v12, 0xbfb8aa3b, v19
	v_exp_f32_e32 v22, v12
	v_pk_mul_f32 v[16:17], v[72:73], v[82:83]
	v_add_f32_e32 v13, 1.0, v13
	v_cvt_pk_bf16_f32 v12, v16, v17
	v_rcp_f32_e32 v16, v13
	v_add_f32_e32 v13, 1.0, v22
	v_pk_fma_f32 v[22:23], v[40:41], v[78:79], v[48:49]
	v_rcp_f32_e32 v17, v13
	v_pk_fma_f32 v[22:23], v[52:53], v[36:37], v[22:23]
	v_lshlrev_b32_e32 v72, 16, v14
	v_and_b32_e32 v73, 0xffff0000, v14
	v_pk_fma_f32 v[22:23], v[44:45], v[72:73], v[22:23]
	v_pk_mul_f32 v[16:17], v[18:19], v[16:17]
	v_mul_f32_e32 v13, 0xbfb8aa3b, v22
	v_exp_f32_e32 v13, v13
	v_mul_f32_e32 v14, 0xbfb8aa3b, v23
	v_exp_f32_e32 v27, v14
	v_pk_fma_f32 v[18:19], v[42:43], v[80:81], v[50:51]
	v_lshlrev_b32_e32 v74, 16, v15
	v_pk_fma_f32 v[18:19], v[54:55], v[28:29], v[18:19]
	v_and_b32_e32 v75, 0xffff0000, v15
	v_pk_fma_f32 v[18:19], v[46:47], v[74:75], v[18:19]
	v_add_f32_e32 v13, 1.0, v13
	v_mul_f32_e32 v15, 0xbfb8aa3b, v18
	v_rcp_f32_e32 v14, v13
	v_add_f32_e32 v13, 1.0, v27
	v_exp_f32_e32 v27, v15
	v_mul_f32_e32 v15, 0xbfb8aa3b, v19
; __device__ __forceinline__ unsigned cvtpk(float lo, float hi) { f32x2_t v = {lo, hi}; bf16x2_t b = __builtin_convertvector(v, bf16x2_t); return __builtin_bit_cast(unsigned, b); }
; __device__ __forceinline__ float lo16(unsigned u) { return __uint_as_float(u << 16); }
; __device__ __forceinline__ float hi16(unsigned u) { return __uint_as_float(u & 0xffff0000u); }
; __device__ __forceinline__ float silu_fast(float v) { return v * __builtin_amdgcn_rcpf(1.f + __builtin_amdgcn_exp2f(-v * LOG2E)); }
; __device__ __forceinline__ unsigned cvtpk(float lo, float hi) { f32x2_t v = {lo, hi}; bf16x2_t b = __builtin_convertvector(v, bf16x2_t); return __builtin_bit_cast(unsigned, b); }
; __device__ __forceinline__ float lo16(unsigned u) { return __uint_as_float(u << 16); }
; __device__ __forceinline__ float hi16(unsigned u) { return __uint_as_float(u & 0xffff0000u); }
; __device__ __forceinline__ float silu_fast(float v) { return v * __builtin_amdgcn_rcpf(1.f + __builtin_amdgcn_exp2f(-v * LOG2E)); }
; template <class Put>
; __device__ __forceinline__ void conv_compute(const ConvRaw& R, const float* cw, const float* cb, int col0, int rg, const Put& put) {
;     ...
;     for (int rr = 0; rr < 8; ++rr) {
;         const u32x4 xm = R.r[rr], x0 = R.r[rr + 1], xp = R.r[rr + 2]; u32x4 o;
; #pragma unroll
;         for (int e = 0; e < 4; ++e) {
;             const float wl0 = e < 2 ? w0a[2 * e] : w0b[2 * e - 4], wh0 = e < 2 ? w0a[2 * e + 1] : w0b[2 * e - 3];
;             const float wl1 = e < 2 ? w1a[2 * e] : w1b[2 * e - 4], wh1 = e < 2 ? w1a[2 * e + 1] : w1b[2 * e - 3];
;             const float wl2 = e < 2 ? w2a[2 * e] : w2b[2 * e - 4], wh2 = e < 2 ? w2a[2 * e + 1] : w2b[2 * e - 3];
;             const float bl = e < 2 ? ba[2 * e] : bb[2 * e - 4], bh = e < 2 ? ba[2 * e + 1] : bb[2 * e - 3];
;             const float vl = bl + wl0 * lo16(xm[e]) + wl1 * lo16(x0[e]) + wl2 * lo16(xp[e]);
;             const float vh = bh + wh0 * hi16(xm[e]) + wh1 * hi16(x0[e]) + wh2 * hi16(xp[e]);
;             o[e] = cvtpk(silu_fast(vl), silu_fast(vh));
;         }
;         put(r0 + rr, o);
;     }
	v_exp_f32_e32 v31, v15
	v_rcp_f32_e32 v15, v13
	v_add_f32_e32 v13, 1.0, v27
	v_rcp_f32_e32 v78, v13
	v_add_f32_e32 v13, 1.0, v31
	v_rcp_f32_e32 v79, v13
	v_cvt_pk_bf16_f32 v13, v16, v17
	v_pk_mul_f32 v[14:15], v[22:23], v[14:15]
	v_and_b32_e32 v23, 0xffff0000, v9
	v_pk_mul_f32 v[16:17], v[18:19], v[78:79]
	v_cvt_pk_bf16_f32 v14, v14, v15
	v_cvt_pk_bf16_f32 v15, v16, v17
	v_pk_fma_f32 v[16:17], v[56:57], v[38:39], v[60:61]
	v_lshlrev_b32_e32 v18, 16, v8
	v_pk_fma_f32 v[16:17], v[64:65], v[76:77], v[16:17]
	v_and_b32_e32 v19, 0xffff0000, v8
	v_pk_fma_f32 v[16:17], v[68:69], v[18:19], v[16:17]
	ds_write_b128 v30, v[12:15] offset:192
	v_mul_f32_e32 v8, 0xbfb8aa3b, v16
	v_exp_f32_e32 v8, v8
	v_mul_f32_e32 v22, 0xbfb8aa3b, v17
	v_exp_f32_e32 v22, v22
	v_pk_fma_f32 v[14:15], v[58:59], v[24:25], v[62:63]
	v_add_f32_e32 v8, 1.0, v8
	v_rcp_f32_e32 v12, v8
	v_add_f32_e32 v8, 1.0, v22
	v_pk_fma_f32 v[14:15], v[66:67], v[20:21], v[14:15]
	v_lshlrev_b32_e32 v22, 16, v9
	v_pk_fma_f32 v[14:15], v[70:71], v[22:23], v[14:15]
	v_rcp_f32_e32 v13, v8
	v_mul_f32_e32 v8, 0xbfb8aa3b, v14
	v_exp_f32_e32 v24, v8
	v_mul_f32_e32 v8, 0xbfb8aa3b, v15
	v_exp_f32_e32 v25, v8
	v_pk_mul_f32 v[8:9], v[16:17], v[12:13]
	v_pk_fma_f32 v[16:17], v[40:41], v[36:37], v[48:49]
	v_add_f32_e32 v12, 1.0, v24
	v_add_f32_e32 v13, 1.0, v25
	v_pk_fma_f32 v[16:17], v[52:53], v[72:73], v[16:17]
	v_lshlrev_b32_e32 v24, 16, v10
	v_and_b32_e32 v25, 0xffff0000, v10
	v_pk_fma_f32 v[16:17], v[44:45], v[24:25], v[16:17]
	v_rcp_f32_e32 v12, v12
	v_mul_f32_e32 v10, 0xbfb8aa3b, v16
	v_exp_f32_e32 v10, v10
	v_mul_f32_e32 v27, 0xbfb8aa3b, v17
	v_exp_f32_e32 v27, v27
	v_rcp_f32_e32 v13, v13
	v_add_f32_e32 v10, 1.0, v10
	v_rcp_f32_e32 v36, v10
	v_add_f32_e32 v10, 1.0, v27
	v_rcp_f32_e32 v37, v10
	v_pk_mul_f32 v[12:13], v[14:15], v[12:13]
	v_pk_fma_f32 v[14:15], v[42:43], v[28:29], v[50:51]
	v_cvt_pk_bf16_f32 v8, v8, v9
	v_cvt_pk_bf16_f32 v9, v12, v13
	v_pk_mul_f32 v[12:13], v[16:17], v[36:37]
	v_pk_fma_f32 v[14:15], v[54:55], v[74:75], v[14:15]
	v_lshlrev_b32_e32 v16, 16, v11
	v_and_b32_e32 v17, 0xffff0000, v11
	v_pk_fma_f32 v[14:15], v[46:47], v[16:17], v[14:15]
	v_pk_fma_f32 v[28:29], v[56:57], v[76:77], v[60:61]
	v_mul_f32_e32 v10, 0xbfb8aa3b, v14
	v_exp_f32_e32 v11, v10
	v_mul_f32_e32 v10, 0xbfb8aa3b, v15
	v_exp_f32_e32 v27, v10
	v_pk_fma_f32 v[28:29], v[64:65], v[18:19], v[28:29]
	v_lshlrev_b32_e32 v36, 16, v4
	v_and_b32_e32 v37, 0xffff0000, v4
	v_add_f32_e32 v11, 1.0, v11
	v_pk_fma_f32 v[28:29], v[68:69], v[36:37], v[28:29]
	v_cvt_pk_bf16_f32 v10, v12, v13
	v_rcp_f32_e32 v12, v11
	v_add_f32_e32 v11, 1.0, v27
	v_mul_f32_e32 v13, 0xbfb8aa3b, v29
	v_exp_f32_e32 v27, v13
	v_rcp_f32_e32 v13, v11
	v_mul_f32_e32 v4, 0xbfb8aa3b, v28
	v_exp_f32_e32 v4, v4
	v_pk_mul_f32 v[12:13], v[14:15], v[12:13]
	s_nop 0
	v_cvt_pk_bf16_f32 v11, v12, v13
	ds_write_b128 v30, v[8:11] offset:256
	v_pk_fma_f32 v[10:11], v[58:59], v[20:21], v[62:63]
	v_add_f32_e32 v4, 1.0, v4
	v_pk_fma_f32 v[10:11], v[66:67], v[22:23], v[10:11]
	v_lshlrev_b32_e32 v12, 16, v5
	v_and_b32_e32 v13, 0xffff0000, v5
	v_rcp_f32_e32 v38, v4
	v_add_f32_e32 v4, 1.0, v27
	v_pk_fma_f32 v[10:11], v[70:71], v[12:13], v[10:11]
	v_rcp_f32_e32 v39, v4
	v_mul_f32_e32 v4, 0xbfb8aa3b, v10
	v_exp_f32_e32 v5, v4
	v_mul_f32_e32 v4, 0xbfb8aa3b, v11
	v_exp_f32_e32 v14, v4
	v_pk_mul_f32 v[8:9], v[28:29], v[38:39]
	v_add_f32_e32 v5, 1.0, v5
	v_cvt_pk_bf16_f32 v4, v8, v9
	v_rcp_f32_e32 v8, v5
	v_add_f32_e32 v5, 1.0, v14
	v_pk_fma_f32 v[14:15], v[40:41], v[72:73], v[48:49]
	v_rcp_f32_e32 v9, v5
	v_pk_fma_f32 v[14:15], v[52:53], v[24:25], v[14:15]
	v_lshlrev_b32_e32 v20, 16, v6
	v_and_b32_e32 v21, 0xffff0000, v6
	v_pk_fma_f32 v[14:15], v[44:45], v[20:21], v[14:15]
	v_pk_mul_f32 v[8:9], v[10:11], v[8:9]
	v_mul_f32_e32 v5, 0xbfb8aa3b, v14
	v_exp_f32_e32 v5, v5
	v_mul_f32_e32 v6, 0xbfb8aa3b, v15
	v_exp_f32_e32 v27, v6
	v_pk_fma_f32 v[10:11], v[42:43], v[74:75], v[50:51]
	v_lshlrev_b32_e32 v28, 16, v7
	v_pk_fma_f32 v[10:11], v[54:55], v[16:17], v[10:11]
	v_and_b32_e32 v29, 0xffff0000, v7
	v_pk_fma_f32 v[10:11], v[46:47], v[28:29], v[10:11]
	v_add_f32_e32 v5, 1.0, v5
	v_mul_f32_e32 v7, 0xbfb8aa3b, v10
	v_rcp_f32_e32 v6, v5
	v_add_f32_e32 v5, 1.0, v27
	v_exp_f32_e32 v27, v7
	v_mul_f32_e32 v7, 0xbfb8aa3b, v11
	v_exp_f32_e32 v31, v7
	v_rcp_f32_e32 v7, v5
	v_add_f32_e32 v5, 1.0, v27
	v_rcp_f32_e32 v38, v5
	v_add_f32_e32 v5, 1.0, v31
	v_rcp_f32_e32 v39, v5
	v_cvt_pk_bf16_f32 v5, v8, v9
	v_pk_mul_f32 v[6:7], v[14:15], v[6:7]
	v_and_b32_e32 v15, 0xffff0000, v1
	v_pk_mul_f32 v[8:9], v[10:11], v[38:39]
	v_cvt_pk_bf16_f32 v6, v6, v7
	v_cvt_pk_bf16_f32 v7, v8, v9
	v_pk_fma_f32 v[8:9], v[56:57], v[18:19], v[60:61]
	v_lshlrev_b32_e32 v10, 16, v0
	v_pk_fma_f32 v[8:9], v[64:65], v[36:37], v[8:9]
	v_and_b32_e32 v11, 0xffff0000, v0
	v_pk_fma_f32 v[8:9], v[68:69], v[10:11], v[8:9]
	ds_write_b128 v30, v[4:7] offset:320
	v_mul_f32_e32 v0, 0xbfb8aa3b, v8
	v_exp_f32_e32 v0, v0
	v_mul_f32_e32 v14, 0xbfb8aa3b, v9
	v_exp_f32_e32 v14, v14
	v_pk_fma_f32 v[6:7], v[58:59], v[22:23], v[62:63]
	v_add_f32_e32 v0, 1.0, v0
	v_rcp_f32_e32 v4, v0
	v_add_f32_e32 v0, 1.0, v14
	v_pk_fma_f32 v[6:7], v[66:67], v[12:13], v[6:7]
	v_lshlrev_b32_e32 v14, 16, v1
	v_pk_fma_f32 v[6:7], v[70:71], v[14:15], v[6:7]
	v_rcp_f32_e32 v5, v0
	v_mul_f32_e32 v0, 0xbfb8aa3b, v6
	v_exp_f32_e32 v18, v0
	v_mul_f32_e32 v0, 0xbfb8aa3b, v7
	v_exp_f32_e32 v19, v0
	v_pk_mul_f32 v[0:1], v[8:9], v[4:5]
	v_pk_fma_f32 v[8:9], v[40:41], v[24:25], v[48:49]
	v_add_f32_e32 v4, 1.0, v18
	v_add_f32_e32 v5, 1.0, v19
	v_pk_fma_f32 v[8:9], v[52:53], v[20:21], v[8:9]
	v_lshlrev_b32_e32 v18, 16, v2
	v_and_b32_e32 v19, 0xffff0000, v2
; #define LAS __attribute__((address_space(3)))
; __device__ __forceinline__ void states_unit(Frame& F, const Ptrs& P, int b, int c, int g, int hh) {
;     ...
;         conv_compute(Rx, P.conv_w, P.conv_b, (h0 + hlx) * 64 + 8 * chx, rgx, PutTr{lds + L_XS + hlx * 16384, chx});
;     }
;     __syncthreads();
;     const int hl = wid >> 1, ph = wid & 1;
;     const int lbase = (int)(unsigned)(size_t)lds + ((lane >> 4) & 1) * 32 + (lane & 3) * 8 + (4 * hi + ((lane & 15) >> 2)) * 64;
;     const LAS float* Wf = (const LAS float*)(lds + L_VEC) + (hl * 2 + 0) * 512 + 384; const LAS float* Wb = (const LAS float*)(lds + L_VEC) + (hl * 2 + 1) * 512 + 384;
;     f32x16 af[4], ab[4];
; #pragma unroll
;     for (int i = 0; i < 4; ++i) { af[i] = f32x16{}; ab[i] = f32x16{}; }
	v_pk_fma_f32 v[8:9], v[44:45], v[18:19], v[8:9]
	v_rcp_f32_e32 v4, v4
	v_mul_f32_e32 v2, 0xbfb8aa3b, v8
	v_exp_f32_e32 v2, v2
	v_mul_f32_e32 v22, 0xbfb8aa3b, v9
	v_exp_f32_e32 v23, v22
	v_rcp_f32_e32 v5, v5
	v_add_f32_e32 v2, 1.0, v2
	v_rcp_f32_e32 v22, v2
	v_add_f32_e32 v2, 1.0, v23
	v_rcp_f32_e32 v23, v2
	v_pk_mul_f32 v[4:5], v[6:7], v[4:5]
	v_pk_fma_f32 v[6:7], v[42:43], v[16:17], v[50:51]
	v_cvt_pk_bf16_f32 v0, v0, v1
	v_cvt_pk_bf16_f32 v1, v4, v5
	v_pk_mul_f32 v[4:5], v[8:9], v[22:23]
	v_pk_fma_f32 v[6:7], v[54:55], v[28:29], v[6:7]
	v_lshlrev_b32_e32 v8, 16, v3
	v_and_b32_e32 v9, 0xffff0000, v3
	v_pk_fma_f32 v[6:7], v[46:47], v[8:9], v[6:7]
	v_pk_fma_f32 v[22:23], v[56:57], v[36:37], v[60:61]
	v_mul_f32_e32 v2, 0xbfb8aa3b, v6
	v_exp_f32_e32 v3, v2
	v_mul_f32_e32 v2, 0xbfb8aa3b, v7
	v_exp_f32_e32 v16, v2
	v_cvt_pk_bf16_f32 v2, v4, v5
	v_add_f32_e32 v3, 1.0, v3
	v_rcp_f32_e32 v4, v3
	v_add_f32_e32 v3, 1.0, v16
	v_lshlrev_b32_e32 v16, 16, v34
	v_and_b32_e32 v17, 0xffff0000, v34
	v_pk_fma_f32 v[10:11], v[64:65], v[10:11], v[22:23]
	s_nop 0
	v_pk_fma_f32 v[10:11], v[68:69], v[16:17], v[10:11]
	s_nop 0
	v_mul_f32_e32 v5, 0xbfb8aa3b, v10
	v_exp_f32_e32 v16, v5
	v_mul_f32_e32 v5, 0xbfb8aa3b, v11
	v_exp_f32_e32 v17, v5
	v_rcp_f32_e32 v5, v3
	v_add_f32_e32 v3, 1.0, v16
	v_rcp_f32_e32 v16, v3
	v_add_f32_e32 v3, 1.0, v17
	v_pk_mul_f32 v[4:5], v[6:7], v[4:5]
	v_rcp_f32_e32 v17, v3
	v_cvt_pk_bf16_f32 v3, v4, v5
	v_pk_fma_f32 v[4:5], v[58:59], v[12:13], v[62:63]
	ds_write_b128 v30, v[0:3] offset:384
	v_lshlrev_b32_e32 v2, 16, v33
	v_and_b32_e32 v3, 0xffff0000, v33
	v_pk_fma_f32 v[4:5], v[66:67], v[14:15], v[4:5]
	v_pk_mul_f32 v[0:1], v[10:11], v[16:17]
	v_pk_fma_f32 v[2:3], v[70:71], v[2:3], v[4:5]
	v_pk_fma_f32 v[10:11], v[40:41], v[20:21], v[48:49]
	v_mul_f32_e32 v4, 0xbfb8aa3b, v2
	v_exp_f32_e32 v4, v4
	v_mul_f32_e32 v5, 0xbfb8aa3b, v3
	v_exp_f32_e32 v5, v5
	v_cvt_pk_bf16_f32 v0, v0, v1
	v_add_f32_e32 v1, 1.0, v4
	v_lshlrev_b32_e32 v6, 16, v32
	v_and_b32_e32 v7, 0xffff0000, v32
	v_pk_fma_f32 v[10:11], v[52:53], v[18:19], v[10:11]
	v_rcp_f32_e32 v4, v1
	v_add_f32_e32 v1, 1.0, v5
	v_pk_fma_f32 v[6:7], v[44:45], v[6:7], v[10:11]
	v_rcp_f32_e32 v5, v1
	v_mul_f32_e32 v1, 0xbfb8aa3b, v6
	v_exp_f32_e32 v1, v1
	v_mul_f32_e32 v10, 0xbfb8aa3b, v7
	v_exp_f32_e32 v10, v10
	v_pk_mul_f32 v[2:3], v[2:3], v[4:5]
	v_add_f32_e32 v1, 1.0, v1
	v_rcp_f32_e32 v4, v1
	v_add_f32_e32 v1, 1.0, v10
	v_pk_fma_f32 v[10:11], v[42:43], v[28:29], v[50:51]
	v_mov_b32_e32 v48, 0
	v_pk_fma_f32 v[8:9], v[54:55], v[8:9], v[10:11]
	v_lshlrev_b32_e32 v10, 16, v26
	v_and_b32_e32 v11, 0xffff0000, v26
	v_pk_fma_f32 v[8:9], v[46:47], v[10:11], v[8:9]
	v_mov_b32_e32 v49, v48
	v_mul_f32_e32 v5, 0xbfb8aa3b, v8
	v_exp_f32_e32 v10, v5
	v_mul_f32_e32 v5, 0xbfb8aa3b, v9
	v_exp_f32_e32 v11, v5
	v_rcp_f32_e32 v5, v1
	v_add_f32_e32 v1, 1.0, v10
	v_rcp_f32_e32 v10, v1
	v_add_f32_e32 v1, 1.0, v11
	v_rcp_f32_e32 v11, v1
	v_cvt_pk_bf16_f32 v1, v2, v3
	v_pk_mul_f32 v[2:3], v[6:7], v[4:5]
	v_mov_b32_e32 v50, v48
	v_pk_mul_f32 v[4:5], v[8:9], v[10:11]
	v_cvt_pk_bf16_f32 v2, v2, v3
	v_cvt_pk_bf16_f32 v3, v4, v5
	ds_write_b128 v30, v[0:3] offset:448
	v_lshlrev_b32_e32 v0, 1, v100
	v_lshlrev_b32_e32 v1, 3, v100
	v_lshlrev_b32_e32 v2, 8, v128
	v_and_b32_e32 v3, 0xc0, v141
	v_and_b32_e32 v0, 32, v0
	v_and_b32_e32 v1, 24, v1
	v_add3_u32 v4, v2, 0, v3
	v_add3_u32 v2, s76, v2, v3
	v_add3_u32 v143, v4, v0, v1
	v_add3_u32 v144, v2, v0, v1
	v_mov_b32_e32 v51, v48
	v_mov_b32_e32 v52, v48
	v_mov_b32_e32 v53, v48
	v_mov_b32_e32 v54, v48
	v_mov_b32_e32 v55, v48
	v_mov_b32_e32 v56, v48
	v_mov_b32_e32 v57, v48
	v_mov_b32_e32 v58, v48
	v_mov_b32_e32 v59, v48
	v_mov_b32_e32 v60, v48
	v_mov_b32_e32 v61, v48
	v_mov_b32_e32 v62, v48
	v_mov_b32_e32 v63, v48
	v_mov_b32_e32 v32, v48
	v_mov_b32_e32 v33, v48
	v_mov_b32_e32 v34, v48
	v_mov_b32_e32 v35, v48
	v_mov_b32_e32 v36, v48
	v_mov_b32_e32 v37, v48
	v_mov_b32_e32 v38, v48
	v_mov_b32_e32 v39, v48
	v_mov_b32_e32 v40, v48
	v_mov_b32_e32 v41, v48
	v_mov_b32_e32 v42, v48
	v_mov_b32_e32 v43, v48
	v_mov_b32_e32 v44, v48
	v_mov_b32_e32 v45, v48
	v_mov_b32_e32 v46, v48
	v_mov_b32_e32 v47, v48
	v_mov_b32_e32 v16, v48
	v_mov_b32_e32 v17, v48
	v_mov_b32_e32 v18, v48
	v_mov_b32_e32 v19, v48
	v_mov_b32_e32 v20, v48
	v_mov_b32_e32 v21, v48
	v_mov_b32_e32 v22, v48
	v_mov_b32_e32 v23, v48
	v_mov_b32_e32 v24, v48
	v_mov_b32_e32 v25, v48
	v_mov_b32_e32 v26, v48
	v_mov_b32_e32 v27, v48
	v_mov_b32_e32 v28, v48
	v_mov_b32_e32 v29, v48
	v_mov_b32_e32 v30, v48
	v_mov_b32_e32 v31, v48
	v_mov_b32_e32 v0, v48
	v_mov_b32_e32 v1, v48
	v_mov_b32_e32 v2, v48
	v_mov_b32_e32 v3, v48
	v_mov_b32_e32 v4, v48
	v_mov_b32_e32 v5, v48
	v_mov_b32_e32 v6, v48
	v_mov_b32_e32 v7, v48
	v_mov_b32_e32 v8, v48
	v_mov_b32_e32 v9, v48
	v_mov_b32_e32 v10, v48
	v_mov_b32_e32 v11, v48
	v_mov_b32_e32 v12, v48
	v_mov_b32_e32 v13, v48
	v_mov_b32_e32 v14, v48
	v_mov_b32_e32 v15, v48
	v_mov_b32_e32 v112, v48
	v_mov_b32_e32 v113, v48
	v_mov_b32_e32 v114, v48
	v_mov_b32_e32 v115, v48
	v_mov_b32_e32 v116, v48
	v_mov_b32_e32 v117, v48
	v_mov_b32_e32 v118, v48
	v_mov_b32_e32 v119, v48
	v_mov_b32_e32 v120, v48
	v_mov_b32_e32 v121, v48
	v_mov_b32_e32 v122, v48
	v_mov_b32_e32 v123, v48
	v_mov_b32_e32 v124, v48
	v_mov_b32_e32 v125, v48
	v_mov_b32_e32 v126, v48
	v_mov_b32_e32 v127, v48
	v_mov_b32_e32 v96, v48
	v_mov_b32_e32 v97, v48
	v_mov_b32_e32 v98, v48
	v_mov_b32_e32 v99, v48
	v_mov_b32_e32 v100, v48
	v_mov_b32_e32 v101, v48
	v_mov_b32_e32 v102, v48
	v_mov_b32_e32 v103, v48
	v_mov_b32_e32 v104, v48
	v_mov_b32_e32 v105, v48
	v_mov_b32_e32 v106, v48
	v_mov_b32_e32 v107, v48
	v_mov_b32_e32 v108, v48
	v_mov_b32_e32 v109, v48
	v_mov_b32_e32 v110, v48
	v_mov_b32_e32 v111, v48
	v_mov_b32_e32 v80, v48
	v_mov_b32_e32 v81, v48
	v_mov_b32_e32 v82, v48
	v_mov_b32_e32 v83, v48
	v_mov_b32_e32 v84, v48
	v_mov_b32_e32 v85, v48
	v_mov_b32_e32 v86, v48
	v_mov_b32_e32 v87, v48
	v_mov_b32_e32 v88, v48
	v_mov_b32_e32 v89, v48
	v_mov_b32_e32 v90, v48
	v_mov_b32_e32 v91, v48
	v_mov_b32_e32 v92, v48
	v_mov_b32_e32 v93, v48
	v_mov_b32_e32 v94, v48
	v_mov_b32_e32 v95, v48
	v_mov_b32_e32 v64, v48
	v_mov_b32_e32 v65, v48
	v_mov_b32_e32 v66, v48
	v_mov_b32_e32 v67, v48
	v_mov_b32_e32 v68, v48
	v_mov_b32_e32 v69, v48
	v_mov_b32_e32 v70, v48
	v_mov_b32_e32 v71, v48
	v_mov_b32_e32 v72, v48
	v_mov_b32_e32 v73, v48
	v_mov_b32_e32 v74, v48
	v_mov_b32_e32 v75, v48
	v_mov_b32_e32 v76, v48
	v_mov_b32_e32 v77, v48
	v_mov_b32_e32 v78, v48
	v_mov_b32_e32 v79, v48
	s_waitcnt lgkmcnt(0)
	s_barrier
	.p2align	6

; #define LAS __attribute__((address_space(3)))
;     __device__ __forceinline__ int lane_() const { return hw_lane(); }
; __device__ __forceinline__ void attn_unit(Frame& F, const Ptrs& P, int u, int u_next, bf16x8 (&qa)[4], ScanRider& R) {
;     ...
;     int lane = F.lane_(); asm volatile("" : "+v"(lane));
;     const int b = u >> 8, nb = u & 63, kvh = (u >> 6) & 3;
;     const int wid = F.wave, r32 = lane & 31, hi = lane >> 5;
;     LAS unsigned char* lds = F.lds;
;     const int hq = kvh * 4 + (wid >> 1), jlo = wid & 1, r0 = 64 * jlo;
;     const size_t qrow = (size_t)b * SEQ + nb * 128 + r0;
;     bf16* Qw = (bf16*)(P.ws + WS_YG) + (qrow + r32) * 2048 + 1024 + hq * 64;
;     const bf16* Gb = (const bf16*)(P.ws + WS_G); float* SSQ = (float*)(P.ws + WS_SSQ);
;     LAS bf16x8* qbl = (LAS bf16x8*)(lds + LDS_QB + wid * 4096) + lane;
;     const float sinkl = P.sink[hq] * LOG2E;
;     const LAS unsigned char* vb0 = lds + LDS_V + ((lane >> 4) & 1) * 32 + (lane & 3) * 8 + (4 * hi + ((lane & 15) >> 2)) * 64;
;     asm volatile("s_waitcnt vmcnt(0)" ::: "memory");
;     __syncthreads();
;     const int kmin = nb == 0 ? 128 : 0, kmax = nb == 63 ? 255 : 383;
;     const bool edge_all = (nb == 0 || nb == 63);
;     float mA = sinkl, mB = sinkl, lA = hi == 0 ? 1.f : 0.f, lB = lA;
;     f32x16 oA[2], oB[2]; oA[0] = f32x16{}; oA[1] = f32x16{}; oB[0] = f32x16{}; oB[1] = f32x16{};
; #pragma unroll 1
.LBB0_649:
	s_lshr_b32 s2, s80, 4
	s_and_b32 s79, s2, 12
	s_add_i32 s79, s79, s42
	s_lshl_b32 s2, s79, 2
	v_mbcnt_lo_u32_b32 v80, -1, 0
	v_mbcnt_hi_u32_b32 v80, -1, v80
	v_mov_b32_e32 v0, s2
	global_load_dword v81, v0, s[44:45]
	v_mov_b32_e32 v14, v1
	v_mov_b32_e32 v15, v1
	s_mov_b32 s6, s80
	v_mov_b32_e32 v0, v1
	v_mov_b32_e32 v2, v1
	v_mov_b32_e32 v3, v1
	v_mov_b32_e32 v4, v1
	v_mov_b32_e32 v5, v1
	v_mov_b32_e32 v6, v1
	v_mov_b32_e32 v7, v1
	v_mov_b32_e32 v8, v1
	v_mov_b32_e32 v9, v1
	v_mov_b32_e32 v10, v1
	v_mov_b32_e32 v11, v1
	v_mov_b32_e32 v12, v1
	v_mov_b32_e32 v13, v1
	v_mov_b64_e32 v[46:47], v[14:15]
	v_mov_b64_e32 v[30:31], v[14:15]
	v_mov_b64_e32 v[78:79], v[14:15]
	v_mov_b64_e32 v[62:63], v[14:15]
	s_and_b32 s81, s6, 63
	v_mov_b64_e32 v[44:45], v[12:13]
	v_mov_b64_e32 v[42:43], v[10:11]
	v_mov_b64_e32 v[40:41], v[8:9]
	v_mov_b64_e32 v[38:39], v[6:7]
	v_mov_b64_e32 v[36:37], v[4:5]
	v_mov_b64_e32 v[34:35], v[2:3]
	v_mov_b64_e32 v[32:33], v[0:1]
	v_mov_b64_e32 v[28:29], v[12:13]
	v_mov_b64_e32 v[26:27], v[10:11]
	v_mov_b64_e32 v[24:25], v[8:9]
	v_mov_b64_e32 v[22:23], v[6:7]
	v_mov_b64_e32 v[20:21], v[4:5]
	v_mov_b64_e32 v[18:19], v[2:3]
	v_mov_b64_e32 v[16:17], v[0:1]
	v_mov_b64_e32 v[76:77], v[12:13]
	v_mov_b64_e32 v[74:75], v[10:11]
	v_mov_b64_e32 v[72:73], v[8:9]
	v_mov_b64_e32 v[70:71], v[6:7]
	v_mov_b64_e32 v[68:69], v[4:5]
	v_mov_b64_e32 v[66:67], v[2:3]
	v_mov_b64_e32 v[64:65], v[0:1]
	v_mov_b64_e32 v[60:61], v[12:13]
	v_mov_b64_e32 v[58:59], v[10:11]
	v_mov_b64_e32 v[56:57], v[8:9]
	v_mov_b64_e32 v[54:55], v[6:7]
	v_mov_b64_e32 v[52:53], v[4:5]
	v_mov_b64_e32 v[50:51], v[2:3]
	v_mov_b64_e32 v[48:49], v[0:1]
	v_lshlrev_b32_e32 v0, 4, v80
	v_and_b32_e32 v177, 31, v80
	v_ashrrev_i32_e32 v14, 5, v80
	v_lshlrev_b32_e32 v2, 1, v80
	v_lshlrev_b32_e32 v3, 3, v80
	v_add_u32_e32 v15, s30, v0
	v_and_b32_e32 v0, 0xc0, v0
	s_cmp_eq_u32 s81, 0
	v_cmp_gt_u32_e64 s[2:3], 32, v80
	v_and_b32_e32 v2, 32, v2
	v_and_b32_e32 v4, 24, v3
	v_add_u32_e32 v185, s43, v3
	v_lshlrev_b32_e32 v3, 10, v14
	v_lshlrev_b32_e32 v5, 4, v177
	v_or_b32_e32 v6, s14, v177
	v_lshl_or_b32 v0, v14, 8, v0
	s_waitcnt vmcnt(0)
	s_cselect_b32 s4, 0x80, 0
	s_cmp_eq_u32 s81, 63
	s_movk_i32 s5, 0x17f
	v_cndmask_b32_e64 v173, 0, 1.0, s[2:3]
	v_add3_u32 v195, 0, v3, v5
	v_or_b32_e32 v3, 0x100, v6
	v_or_b32_e32 v5, 32, v6
	v_or_b32_e32 v7, 0x120, v6
	v_or3_b32 v0, v0, v2, v4
	s_cselect_b32 s5, 0xff, s5
	s_mov_b32 s80, 0
	s_mov_b32 s82, 0
	v_lshl_add_u32 v189, v14, 2, s14
	s_waitcnt vmcnt(0)
	v_mul_f32_e32 v201, 0x3fb8aa3b, v81
	v_add_u32_e32 v196, 0, v0
	v_max_u32_e32 v197, s4, v6
	v_max_u32_e32 v198, s4, v5
	v_min_u32_e32 v199, s5, v3
	v_min_u32_e32 v200, s5, v7
	v_mov_b32_e32 v181, v173
	v_mov_b32_e32 v202, v201
	s_barrier
	s_branch .LBB0_651
	.p2align	6

; #define LAS __attribute__((address_space(3)))
; template <class Wait>
; __device__ __forceinline__ void out_unit(Frame& F, const Ptrs& P, int b, int c, int g, const Wait& wait) {
;     ...
; #pragma unroll
;     for (int ks = 0; ks < 8; ++ks) { const int chn = 2 * ks + hi;
;         const bf16x8 c0 = *(const LAS bf16x8*)(crow0 + ((chn ^ (q0 & 15)) * 16)), c1 = *(const LAS bf16x8*)(crow1 + ((chn ^ (q1 & 15)) * 16));
;         y[0][0] = __builtin_amdgcn_mfma_f32_32x32x16_bf16(A0[0][ks], c0, y[0][0], 0, 0, 0); y[0][1] = __builtin_amdgcn_mfma_f32_32x32x16_bf16(A0[0][ks], c1, y[0][1], 0, 0, 0);
;         y[1][0] = __builtin_amdgcn_mfma_f32_32x32x16_bf16(A0[1][ks], c0, y[1][0], 0, 0, 0); y[1][1] = __builtin_amdgcn_mfma_f32_32x32x16_bf16(A0[1][ks], c1, y[1][1], 0, 0, 0); }
.LBB0_742:
	v_add_u32_e32 v121, 0, v121
	v_add_u32_e32 v122, 0, v122
	v_add_u32_e32 v225, v121, v123
	v_add_u32_e32 v226, v122, v123
	ds_read_b128 v[20:23], v225
	ds_read_b128 v[24:27], v226
	v_add_u32_e32 v227, v121, v124
	s_waitcnt vmcnt(15) lgkmcnt(1)
	v_mfma_f32_32x32x16_bf16 v[48:63], v[0:3], v[20:23], 0
	v_add_u32_e32 v228, v122, v124
	ds_read_b128 v[136:139], v227
	ds_read_b128 v[140:143], v228
	v_add_u32_e32 v229, v121, v125
	v_add_u32_e32 v230, v122, v125
	v_add_u32_e32 v231, v121, v126
	v_add_u32_e32 v232, v122, v126
	s_waitcnt lgkmcnt(2)
	v_mfma_f32_32x32x16_bf16 v[0:15], v[0:3], v[24:27], 0
	v_add_u32_e32 v233, v121, v127
	v_add_u32_e32 v234, v122, v127
	v_add_u32_e32 v235, v121, v133
	v_add_u32_e32 v236, v122, v133
	v_add_u32_e32 v237, v121, v134
	v_add_u32_e32 v238, v122, v134
	v_add_u32_e32 v239, v121, v135
	s_waitcnt vmcnt(7)
	v_mfma_f32_32x32x16_bf16 v[32:47], v[16:19], v[20:23], 0
	v_add_u32_e32 v240, v122, v135
	s_mov_b32 s2, 1
	v_mfma_f32_32x32x16_bf16 v[16:31], v[16:19], v[24:27], 0
	s_waitcnt lgkmcnt(1)
	v_mfma_f32_32x32x16_bf16 v[48:63], v[108:111], v[136:139], v[48:63]
	s_waitcnt lgkmcnt(0)
	v_mfma_f32_32x32x16_bf16 v[0:15], v[108:111], v[140:143], v[0:15]
	ds_read_b128 v[108:111], v229
	s_waitcnt vmcnt(6)
	v_mfma_f32_32x32x16_bf16 v[32:47], v[116:119], v[136:139], v[32:47]
	v_mfma_f32_32x32x16_bf16 v[16:31], v[116:119], v[140:143], v[16:31]
	ds_read_b128 v[116:119], v230
	s_waitcnt lgkmcnt(1)
	v_mfma_f32_32x32x16_bf16 v[48:63], v[96:99], v[108:111], v[48:63]
	s_waitcnt lgkmcnt(0)
	v_mfma_f32_32x32x16_bf16 v[0:15], v[96:99], v[116:119], v[0:15]
	ds_read_b128 v[96:99], v231
	s_waitcnt vmcnt(5)
	v_mfma_f32_32x32x16_bf16 v[32:47], v[112:115], v[108:111], v[32:47]
	ds_read_b128 v[108:111], v232
	v_mfma_f32_32x32x16_bf16 v[16:31], v[112:115], v[116:119], v[16:31]
	s_waitcnt lgkmcnt(1)
	v_mfma_f32_32x32x16_bf16 v[48:63], v[84:87], v[96:99], v[48:63]
	s_waitcnt lgkmcnt(0)
	v_mfma_f32_32x32x16_bf16 v[0:15], v[84:87], v[108:111], v[0:15]
	ds_read_b128 v[84:87], v233
	s_waitcnt vmcnt(4)
	v_mfma_f32_32x32x16_bf16 v[32:47], v[104:107], v[96:99], v[32:47]
	ds_read_b128 v[96:99], v234
	v_mfma_f32_32x32x16_bf16 v[16:31], v[104:107], v[108:111], v[16:31]
	v_lshlrev_b32_e32 v106, 2, v223
	s_waitcnt lgkmcnt(1)
	v_mfma_f32_32x32x16_bf16 v[48:63], v[88:91], v[84:87], v[48:63]
	s_waitcnt lgkmcnt(0)
	v_mfma_f32_32x32x16_bf16 v[0:15], v[88:91], v[96:99], v[0:15]
	ds_read_b128 v[88:91], v236
	s_waitcnt vmcnt(3)
	v_mfma_f32_32x32x16_bf16 v[32:47], v[100:103], v[84:87], v[32:47]
	ds_read_b128 v[84:87], v235
	v_mfma_f32_32x32x16_bf16 v[16:31], v[100:103], v[96:99], v[16:31]
	s_waitcnt lgkmcnt(0)
	v_mfma_f32_32x32x16_bf16 v[48:63], v[76:79], v[84:87], v[48:63]
	v_mfma_f32_32x32x16_bf16 v[0:15], v[76:79], v[88:91], v[0:15]
	ds_read_b128 v[76:79], v237
	s_waitcnt vmcnt(2)
	v_mfma_f32_32x32x16_bf16 v[32:47], v[92:95], v[84:87], v[32:47]
	ds_read_b128 v[84:87], v238
	v_mfma_f32_32x32x16_bf16 v[16:31], v[92:95], v[88:91], v[16:31]
	s_waitcnt lgkmcnt(1)
	v_mfma_f32_32x32x16_bf16 v[48:63], v[68:71], v[76:79], v[48:63]
	s_waitcnt lgkmcnt(0)
	v_mfma_f32_32x32x16_bf16 v[0:15], v[68:71], v[84:87], v[0:15]
	ds_read_b128 v[68:71], v239
	s_waitcnt vmcnt(1)
	v_mfma_f32_32x32x16_bf16 v[32:47], v[80:83], v[76:79], v[32:47]
	ds_read_b128 v[76:79], v240
	v_mfma_f32_32x32x16_bf16 v[16:31], v[80:83], v[84:87], v[16:31]
	s_waitcnt lgkmcnt(1)
	v_mfma_f32_32x32x16_bf16 v[48:63], v[64:67], v[68:71], v[48:63]
	s_waitcnt lgkmcnt(0)
	v_mfma_f32_32x32x16_bf16 v[0:15], v[64:67], v[76:79], v[0:15]
	v_lshlrev_b32_e32 v64, 1, v224
	v_and_b32_e32 v80, 32, v64
	v_lshlrev_b32_e32 v64, 3, v224
	v_and_b32_e32 v81, 24, v64
	s_waitcnt vmcnt(0)
; #define SSD_SBAR() __builtin_amdgcn_sched_barrier(0)
; template <class Wait>
; __device__ __forceinline__ void out_unit(Frame& F, const Ptrs& P, int b, int c, int g, const Wait& wait) {
;     ...
;         y[1][0] = __builtin_amdgcn_mfma_f32_32x32x16_bf16(A0[1][ks], c0, y[1][0], 0, 0, 0); y[1][1] = __builtin_amdgcn_mfma_f32_32x32x16_bf16(A0[1][ks], c1, y[1][1], 0, 0, 0); }
;     SSD_SBAR();
;     bf16x8 A1[2][8];
;     { const unsigned char* blk = SB + ((((size_t)b * 64 + c) * 2 + 1) * 16 + h) * 16384 + hi * 512 + r32 * 16;
; #pragma unroll
;       for (int pb = 0; pb < 2; ++pb)
; #pragma unroll
;           for (int ks = 0; ks < 8; ++ks) A1[pb][ks] = *(const bf16x8*)(blk + (pb * 8 + ks) * 1024); }
;     const size_t rowq0 = (size_t)b * SEQ + c * 128 + q0;
;     { const float e0 = __builtin_amdgcn_exp2f(Vf[q0]), e1 = __builtin_amdgcn_exp2f(Vf[q1]);
; #pragma unroll
;       for (int pb = 0; pb < 2; ++pb)
; #pragma unroll
;           for (int r = 0; r < 16; ++r) { y[pb][0][r] *= e0; y[pb][1][r] *= e1; } }
;     {
;         const float afq0 = Vf[q0], afq1 = Vf[q1], abq0 = Vb[q0], abq1 = Vb[q1];
	v_mfma_f32_32x32x16_bf16 v[32:47], v[72:75], v[68:71], v[32:47]
	v_mfma_f32_32x32x16_bf16 v[16:31], v[72:75], v[76:79], v[16:31]
	s_add_u32 s0, s95, s18
	s_addc_u32 s1, s34, 0
	s_lshl_b64 s[0:1], s[0:1], 14
	s_add_u32 s0, s58, s0
	s_addc_u32 s1, s59, s1
	v_lshl_add_u64 v[64:65], s[0:1], 0, v[200:201]
	v_lshl_add_u64 v[72:73], v[64:65], 0, v[128:129]
	v_add_co_u32_e32 v74, vcc, s88, v72
	global_load_dwordx4 v[64:67], v[72:73], off
	global_load_dwordx4 v[168:171], v[72:73], off offset:1024
	global_load_dwordx4 v[156:159], v[72:73], off offset:2048
	global_load_dwordx4 v[148:151], v[72:73], off offset:3072
	v_addc_co_u32_e32 v75, vcc, 0, v73, vcc
	v_add_co_u32_e32 v76, vcc, s89, v72
	v_or_b32_e32 v104, s82, v222
	s_nop 0
	v_addc_co_u32_e32 v77, vcc, 0, v73, vcc
	global_load_dwordx4 v[144:147], v[74:75], off offset:1024
	global_load_dwordx4 v[136:139], v[74:75], off offset:2048
	global_load_dwordx4 v[164:167], v[76:77], off offset:-4096
	global_load_dwordx4 v[68:71], v[76:77], off
	global_load_dwordx4 v[188:191], v[76:77], off offset:1024
	global_load_dwordx4 v[184:187], v[76:77], off offset:2048
	global_load_dwordx4 v[176:179], v[76:77], off offset:3072
	v_add_co_u32_e32 v72, vcc, s90, v72
	s_mov_b32 s3, 0
	s_nop 0
	v_addc_co_u32_e32 v73, vcc, 0, v73, vcc
	global_load_dwordx4 v[140:143], v[74:75], off offset:3072
	global_load_dwordx4 v[180:183], v[72:73], off
	global_load_dwordx4 v[172:175], v[72:73], off offset:1024
	global_load_dwordx4 v[160:163], v[72:73], off offset:2048
	global_load_dwordx4 v[152:155], v[72:73], off offset:3072
	v_lshlrev_b32_e32 v73, 2, v202
	v_add_u32_e32 v72, s73, v73
	ds_read_b32 v128, v72
	v_lshlrev_b32_e32 v75, 2, v120
	v_add_u32_e32 v72, s73, v75
	ds_read_b32 v129, v72
	v_add_u32_e32 v242, s75, v73
	s_waitcnt lgkmcnt(1)
	v_exp_f32_e32 v72, v128
	v_add_u32_e32 v241, s75, v75
	ds_read_b32 v130, v242
	ds_read_b32 v131, v241
	s_waitcnt lgkmcnt(2)
	v_exp_f32_e32 v74, v129
	v_pk_mul_f32 v[62:63], v[62:63], v[72:73] op_sel_hi:[1,0]
	v_pk_mul_f32 v[60:61], v[60:61], v[72:73] op_sel_hi:[1,0]
	v_pk_mul_f32 v[58:59], v[58:59], v[72:73] op_sel_hi:[1,0]
	v_pk_mul_f32 v[56:57], v[56:57], v[72:73] op_sel_hi:[1,0]
	v_pk_mul_f32 v[54:55], v[54:55], v[72:73] op_sel_hi:[1,0]
	v_pk_mul_f32 v[52:53], v[52:53], v[72:73] op_sel_hi:[1,0]
	v_pk_mul_f32 v[50:51], v[50:51], v[72:73] op_sel_hi:[1,0]
	v_pk_mul_f32 v[48:49], v[48:49], v[72:73] op_sel_hi:[1,0]
	v_pk_mul_f32 v[46:47], v[46:47], v[72:73] op_sel_hi:[1,0]
	v_pk_mul_f32 v[44:45], v[44:45], v[72:73] op_sel_hi:[1,0]
	v_pk_mul_f32 v[42:43], v[42:43], v[72:73] op_sel_hi:[1,0]
	v_pk_mul_f32 v[40:41], v[40:41], v[72:73] op_sel_hi:[1,0]
	v_pk_mul_f32 v[38:39], v[38:39], v[72:73] op_sel_hi:[1,0]
	v_pk_mul_f32 v[36:37], v[36:37], v[72:73] op_sel_hi:[1,0]
	v_pk_mul_f32 v[34:35], v[34:35], v[72:73] op_sel_hi:[1,0]
	v_pk_mul_f32 v[32:33], v[32:33], v[72:73] op_sel_hi:[1,0]
	v_lshlrev_b32_e32 v72, 8, v104
	v_lshlrev_b32_e32 v73, 4, v224
	v_add3_u32 v134, 0, v72, v204
	v_lshlrev_b32_e32 v72, 8, v223
	v_and_b32_e32 v73, 0xc0, v73
	v_add3_u32 v72, s76, v72, v73
	v_add3_u32 v135, v72, v80, v81
	v_lshlrev_b32_e32 v72, 4, v223
	v_pk_mul_f32 v[14:15], v[14:15], v[74:75] op_sel_hi:[1,0]
	v_pk_mul_f32 v[12:13], v[12:13], v[74:75] op_sel_hi:[1,0]
	v_pk_mul_f32 v[10:11], v[10:11], v[74:75] op_sel_hi:[1,0]
	v_pk_mul_f32 v[8:9], v[8:9], v[74:75] op_sel_hi:[1,0]
	v_pk_mul_f32 v[6:7], v[6:7], v[74:75] op_sel_hi:[1,0]
	v_pk_mul_f32 v[4:5], v[4:5], v[74:75] op_sel_hi:[1,0]
	v_pk_mul_f32 v[2:3], v[2:3], v[74:75] op_sel_hi:[1,0]
	v_pk_mul_f32 v[0:1], v[0:1], v[74:75] op_sel_hi:[1,0]
	v_pk_mul_f32 v[30:31], v[30:31], v[74:75] op_sel_hi:[1,0]
	v_pk_mul_f32 v[28:29], v[28:29], v[74:75] op_sel_hi:[1,0]
	v_pk_mul_f32 v[26:27], v[26:27], v[74:75] op_sel_hi:[1,0]
	v_pk_mul_f32 v[24:25], v[24:25], v[74:75] op_sel_hi:[1,0]
	v_pk_mul_f32 v[22:23], v[22:23], v[74:75] op_sel_hi:[1,0]
	v_pk_mul_f32 v[20:21], v[20:21], v[74:75] op_sel_hi:[1,0]
	v_pk_mul_f32 v[18:19], v[18:19], v[74:75] op_sel_hi:[1,0]
	v_pk_mul_f32 v[16:17], v[16:17], v[74:75] op_sel_hi:[1,0]
	v_add_u32_e32 v133, v121, v204
	v_mov_b32_e32 v105, v104
	v_mov_b32_e32 v107, v202
	v_add_u32_e32 v192, s74, v72
	v_add_u32_e32 v193, s72, v72
	s_mov_b32 s4, 0
	s_branch .LBB0_744
	.p2align	6
